# snake ordering of MFMAs inside each 8-MFMA group (fewer operand changes between consecutive MFMAs)
# speedup vs baseline: 1.0201x; 1.0201x over previous
.LBB0_169:
	s_add_u32 s34, s50, 0xfff80080
	s_addc_u32 s35, s51, -1
	s_add_i32 s52, 0, 0x10000
	s_cmp_eq_u32 s77, 28
	s_cselect_b32 s55, s36, s35
	s_cselect_b32 s54, s37, s34
	v_add_u32_e32 v145, s52, v142
	s_cselect_b32 s35, s41, s76
	s_cselect_b32 s34, s43, s71
	s_add_i32 s53, 0, 0x14000
	ds_read_b128 v[146:149], v145
	ds_read_b128 v[150:153], v145 offset:1024
	ds_read_b128 v[172:175], v145 offset:2048
	ds_read_b128 v[176:179], v145 offset:3072
	v_add_u32_e32 v145, s53, v142
	ds_read_b128 v[180:183], v145
	ds_read_b128 v[184:187], v145 offset:1024
	ds_read_b128 v[188:191], v145 offset:2048
	ds_read_b128 v[192:195], v145 offset:3072
	v_lshl_add_u64 v[154:155], s[50:51], 0, v[138:139]
	s_add_i32 m0, s57, 0xc000
	ds_read_b128 v[196:199], v144
	ds_read_b128 v[200:203], v144 offset:1024
	ds_read_b128 v[204:207], v144 offset:2048
	ds_read_b128 v[208:211], v144 offset:3072
	ds_read_b128 v[212:215], v144 offset:4096
	ds_read_b128 v[216:219], v144 offset:5120
	ds_read_b128 v[228:231], v144 offset:6144
	ds_read_b128 v[232:235], v144 offset:7168
	global_load_lds_dwordx4 v[154:155], off
	v_lshl_add_u64 v[154:155], s[50:51], 0, v[140:141]
	s_add_i32 m0, s57, 0xe000
	s_nop 0
	global_load_lds_dwordx4 v[154:155], off
	s_waitcnt vmcnt(8)
	s_waitcnt lgkmcnt(0)
	s_barrier
	s_setprio 1
	v_mfma_f32_16x16x32_bf16 v[128:131], v[146:149], v[196:199], v[128:131]
	v_mfma_f32_16x16x32_bf16 v[124:127], v[172:175], v[196:199], v[124:127]
	v_mfma_f32_16x16x32_bf16 v[108:111], v[172:175], v[204:207], v[108:111]
	v_mfma_f32_16x16x32_bf16 v[112:115], v[146:149], v[204:207], v[112:115]
	v_mfma_f32_16x16x32_bf16 v[96:99], v[146:149], v[212:215], v[96:99]
	v_mfma_f32_16x16x32_bf16 v[92:95], v[172:175], v[212:215], v[92:95]
	v_mfma_f32_16x16x32_bf16 v[76:79], v[172:175], v[228:231], v[76:79]
	v_mfma_f32_16x16x32_bf16 v[80:83], v[146:149], v[228:231], v[80:83]
	v_mfma_f32_16x16x32_bf16 v[128:131], v[150:153], v[200:203], v[128:131]
	v_mfma_f32_16x16x32_bf16 v[124:127], v[176:179], v[200:203], v[124:127]
	v_mfma_f32_16x16x32_bf16 v[108:111], v[176:179], v[208:211], v[108:111]
	v_mfma_f32_16x16x32_bf16 v[112:115], v[150:153], v[208:211], v[112:115]
	v_mfma_f32_16x16x32_bf16 v[96:99], v[150:153], v[216:219], v[96:99]
	v_mfma_f32_16x16x32_bf16 v[92:95], v[176:179], v[216:219], v[92:95]
	v_mfma_f32_16x16x32_bf16 v[76:79], v[176:179], v[232:235], v[76:79]
	v_mfma_f32_16x16x32_bf16 v[80:83], v[150:153], v[232:235], v[80:83]
	v_mfma_f32_16x16x32_bf16 v[120:123], v[180:183], v[196:199], v[120:123]
	v_mfma_f32_16x16x32_bf16 v[116:119], v[188:191], v[196:199], v[116:119]
	v_mfma_f32_16x16x32_bf16 v[100:103], v[188:191], v[204:207], v[100:103]
	v_mfma_f32_16x16x32_bf16 v[104:107], v[180:183], v[204:207], v[104:107]
	v_mfma_f32_16x16x32_bf16 v[88:91], v[180:183], v[212:215], v[88:91]
	v_mfma_f32_16x16x32_bf16 v[84:87], v[188:191], v[212:215], v[84:87]
	v_mfma_f32_16x16x32_bf16 v[68:71], v[188:191], v[228:231], v[68:71]
	v_mfma_f32_16x16x32_bf16 v[72:75], v[180:183], v[228:231], v[72:75]
	v_mfma_f32_16x16x32_bf16 v[120:123], v[184:187], v[200:203], v[120:123]
	v_mfma_f32_16x16x32_bf16 v[116:119], v[192:195], v[200:203], v[116:119]
	v_mfma_f32_16x16x32_bf16 v[100:103], v[192:195], v[208:211], v[100:103]
	v_mfma_f32_16x16x32_bf16 v[104:107], v[184:187], v[208:211], v[104:107]
	v_mfma_f32_16x16x32_bf16 v[88:91], v[184:187], v[216:219], v[88:91]
	v_mfma_f32_16x16x32_bf16 v[84:87], v[192:195], v[216:219], v[84:87]
	v_mfma_f32_16x16x32_bf16 v[68:71], v[192:195], v[232:235], v[68:71]
	v_mfma_f32_16x16x32_bf16 v[72:75], v[184:187], v[232:235], v[72:75]
	s_setprio 0
	s_barrier
	s_add_i32 s52, s52, s19
	v_lshl_add_u64 v[154:155], s[34:35], 0, v[134:135]
	s_mov_b32 m0, s52
	ds_read_b128 v[196:199], v144 offset:16384
	ds_read_b128 v[200:203], v144 offset:17408
	ds_read_b128 v[204:207], v144 offset:18432
	ds_read_b128 v[208:211], v144 offset:19456
	ds_read_b128 v[212:215], v144 offset:20480
	ds_read_b128 v[216:219], v144 offset:21504
	ds_read_b128 v[228:231], v144 offset:22528
	ds_read_b128 v[232:235], v144 offset:23552
	global_load_lds_dwordx4 v[154:155], off
	s_add_i32 m0, s52, 0x2000
	s_add_u32 s96, s34, 0x4000
	v_lshl_add_u64 v[154:155], s[34:35], 0, v[0:1]
	s_addc_u32 s97, s35, 0
	s_add_i32 s52, s53, s19
	global_load_lds_dwordx4 v[154:155], off
	v_lshl_add_u64 v[154:155], s[96:97], 0, v[134:135]
	s_mov_b32 m0, s52
	v_lshl_add_u64 v[236:237], s[54:55], 0, v[132:133]
	global_load_lds_dwordx4 v[154:155], off
	v_lshl_add_u64 v[154:155], s[96:97], 0, v[0:1]
	s_add_i32 m0, s52, 0x2000
	s_nop 0
	global_load_lds_dwordx4 v[154:155], off
	v_lshl_add_u64 v[154:155], s[54:55], 0, v[136:137]
	s_mov_b32 m0, s57
	s_nop 0
	global_load_lds_dwordx4 v[154:155], off
	s_mov_b32 m0, s58
	s_nop 0
	global_load_lds_dwordx4 v[236:237], off
	s_waitcnt vmcnt(8)
	s_waitcnt lgkmcnt(0)
	s_barrier
	s_setprio 1
	v_mfma_f32_16x16x32_bf16 v[64:67], v[146:149], v[196:199], v[64:67]
	v_mfma_f32_16x16x32_bf16 v[60:63], v[172:175], v[196:199], v[60:63]
	v_mfma_f32_16x16x32_bf16 v[44:47], v[172:175], v[204:207], v[44:47]
	v_mfma_f32_16x16x32_bf16 v[48:51], v[146:149], v[204:207], v[48:51]
	v_mfma_f32_16x16x32_bf16 v[32:35], v[146:149], v[212:215], v[32:35]
	v_mfma_f32_16x16x32_bf16 v[28:31], v[172:175], v[212:215], v[28:31]
	v_mfma_f32_16x16x32_bf16 v[12:15], v[172:175], v[228:231], v[12:15]
	v_mfma_f32_16x16x32_bf16 v[16:19], v[146:149], v[228:231], v[16:19]
	v_mfma_f32_16x16x32_bf16 v[64:67], v[150:153], v[200:203], v[64:67]
	v_mfma_f32_16x16x32_bf16 v[60:63], v[176:179], v[200:203], v[60:63]
	v_mfma_f32_16x16x32_bf16 v[44:47], v[176:179], v[208:211], v[44:47]
	v_mfma_f32_16x16x32_bf16 v[48:51], v[150:153], v[208:211], v[48:51]
	v_mfma_f32_16x16x32_bf16 v[32:35], v[150:153], v[216:219], v[32:35]
	v_mfma_f32_16x16x32_bf16 v[28:31], v[176:179], v[216:219], v[28:31]
	v_mfma_f32_16x16x32_bf16 v[12:15], v[176:179], v[232:235], v[12:15]
	v_mfma_f32_16x16x32_bf16 v[16:19], v[150:153], v[232:235], v[16:19]
	v_mfma_f32_16x16x32_bf16 v[56:59], v[180:183], v[196:199], v[56:59]
	v_mfma_f32_16x16x32_bf16 v[52:55], v[188:191], v[196:199], v[52:55]
	v_mfma_f32_16x16x32_bf16 v[36:39], v[188:191], v[204:207], v[36:39]
	v_mfma_f32_16x16x32_bf16 v[40:43], v[180:183], v[204:207], v[40:43]
	v_mfma_f32_16x16x32_bf16 v[24:27], v[180:183], v[212:215], v[24:27]
	v_mfma_f32_16x16x32_bf16 v[20:23], v[188:191], v[212:215], v[20:23]
	v_mfma_f32_16x16x32_bf16 v[4:7], v[188:191], v[228:231], v[4:7]
	v_mfma_f32_16x16x32_bf16 v[8:11], v[180:183], v[228:231], v[8:11]
	v_mfma_f32_16x16x32_bf16 v[56:59], v[184:187], v[200:203], v[56:59]
	v_mfma_f32_16x16x32_bf16 v[52:55], v[192:195], v[200:203], v[52:55]
	v_mfma_f32_16x16x32_bf16 v[36:39], v[192:195], v[208:211], v[36:39]
	v_mfma_f32_16x16x32_bf16 v[40:43], v[184:187], v[208:211], v[40:43]
	v_mfma_f32_16x16x32_bf16 v[24:27], v[184:187], v[216:219], v[24:27]
	v_mfma_f32_16x16x32_bf16 v[20:23], v[192:195], v[216:219], v[20:23]
	v_mfma_f32_16x16x32_bf16 v[4:7], v[192:195], v[232:235], v[4:7]
	v_mfma_f32_16x16x32_bf16 v[8:11], v[184:187], v[232:235], v[8:11]
	s_setprio 0
	s_barrier
	s_add_i32 s52, 0, 0x18000
	v_add_u32_e32 v145, s52, v142
	s_add_i32 s53, 0, 0x1c000
	ds_read_b128 v[146:149], v145
	ds_read_b128 v[150:153], v145 offset:1024
	ds_read_b128 v[172:175], v145 offset:2048
	ds_read_b128 v[176:179], v145 offset:3072
	v_add_u32_e32 v145, s53, v142
	ds_read_b128 v[180:183], v145
	ds_read_b128 v[184:187], v145 offset:1024
	ds_read_b128 v[188:191], v145 offset:2048
	ds_read_b128 v[192:195], v145 offset:3072
	s_add_u32 s54, s54, 0x80000
	s_addc_u32 s55, s55, 0
	s_mov_b32 m0, s59
	v_lshl_add_u64 v[238:239], s[54:55], 0, v[136:137]
	ds_read_b128 v[196:199], v144 offset:32768
	ds_read_b128 v[200:203], v144 offset:33792
	ds_read_b128 v[204:207], v144 offset:34816
	ds_read_b128 v[208:211], v144 offset:35840
	ds_read_b128 v[212:215], v144 offset:36864
	ds_read_b128 v[216:219], v144 offset:37888
	ds_read_b128 v[228:231], v144 offset:38912
	ds_read_b128 v[232:235], v144 offset:39936
	global_load_lds_dwordx4 v[238:239], off
	v_lshl_add_u64 v[238:239], s[54:55], 0, v[132:133]
	s_mov_b32 m0, s60
	s_nop 0
	global_load_lds_dwordx4 v[238:239], off
	s_waitcnt vmcnt(8)
	s_waitcnt lgkmcnt(0)
	s_barrier
	s_setprio 1
	v_mfma_f32_16x16x32_bf16 v[128:131], v[146:149], v[196:199], v[128:131]
	v_mfma_f32_16x16x32_bf16 v[124:127], v[172:175], v[196:199], v[124:127]
	v_mfma_f32_16x16x32_bf16 v[108:111], v[172:175], v[204:207], v[108:111]
	v_mfma_f32_16x16x32_bf16 v[112:115], v[146:149], v[204:207], v[112:115]
	v_mfma_f32_16x16x32_bf16 v[96:99], v[146:149], v[212:215], v[96:99]
	v_mfma_f32_16x16x32_bf16 v[92:95], v[172:175], v[212:215], v[92:95]
	v_mfma_f32_16x16x32_bf16 v[76:79], v[172:175], v[228:231], v[76:79]
	v_mfma_f32_16x16x32_bf16 v[80:83], v[146:149], v[228:231], v[80:83]
	v_mfma_f32_16x16x32_bf16 v[128:131], v[150:153], v[200:203], v[128:131]
	v_mfma_f32_16x16x32_bf16 v[124:127], v[176:179], v[200:203], v[124:127]
	v_mfma_f32_16x16x32_bf16 v[108:111], v[176:179], v[208:211], v[108:111]
	v_mfma_f32_16x16x32_bf16 v[112:115], v[150:153], v[208:211], v[112:115]
	v_mfma_f32_16x16x32_bf16 v[96:99], v[150:153], v[216:219], v[96:99]
	v_mfma_f32_16x16x32_bf16 v[92:95], v[176:179], v[216:219], v[92:95]
	v_mfma_f32_16x16x32_bf16 v[76:79], v[176:179], v[232:235], v[76:79]
	v_mfma_f32_16x16x32_bf16 v[80:83], v[150:153], v[232:235], v[80:83]
	v_mfma_f32_16x16x32_bf16 v[120:123], v[180:183], v[196:199], v[120:123]
	v_mfma_f32_16x16x32_bf16 v[116:119], v[188:191], v[196:199], v[116:119]
	v_mfma_f32_16x16x32_bf16 v[100:103], v[188:191], v[204:207], v[100:103]
	v_mfma_f32_16x16x32_bf16 v[104:107], v[180:183], v[204:207], v[104:107]
	v_mfma_f32_16x16x32_bf16 v[88:91], v[180:183], v[212:215], v[88:91]
	v_mfma_f32_16x16x32_bf16 v[84:87], v[188:191], v[212:215], v[84:87]
	v_mfma_f32_16x16x32_bf16 v[68:71], v[188:191], v[228:231], v[68:71]
	v_mfma_f32_16x16x32_bf16 v[72:75], v[180:183], v[228:231], v[72:75]
	v_mfma_f32_16x16x32_bf16 v[120:123], v[184:187], v[200:203], v[120:123]
	v_mfma_f32_16x16x32_bf16 v[116:119], v[192:195], v[200:203], v[116:119]
	v_mfma_f32_16x16x32_bf16 v[100:103], v[192:195], v[208:211], v[100:103]
	v_mfma_f32_16x16x32_bf16 v[104:107], v[184:187], v[208:211], v[104:107]
	v_mfma_f32_16x16x32_bf16 v[88:91], v[184:187], v[216:219], v[88:91]
	v_mfma_f32_16x16x32_bf16 v[84:87], v[192:195], v[216:219], v[84:87]
	v_mfma_f32_16x16x32_bf16 v[68:71], v[192:195], v[232:235], v[68:71]
	v_mfma_f32_16x16x32_bf16 v[72:75], v[184:187], v[232:235], v[72:75]
	s_setprio 0
	s_barrier
	s_add_u32 s54, s34, 0x160000
	s_addc_u32 s55, s35, 0
	s_add_i32 s52, s52, s19
	v_lshl_add_u64 v[238:239], s[54:55], 0, v[134:135]
	s_mov_b32 m0, s52
	ds_read_b128 v[196:199], v144 offset:49152
	ds_read_b128 v[200:203], v144 offset:50176
	ds_read_b128 v[204:207], v144 offset:51200
	ds_read_b128 v[208:211], v144 offset:52224
	ds_read_b128 v[212:215], v144 offset:53248
	ds_read_b128 v[216:219], v144 offset:54272
	ds_read_b128 v[228:231], v144 offset:55296
	ds_read_b128 v[232:235], v144 offset:56320
	global_load_lds_dwordx4 v[238:239], off
	s_add_i32 m0, s52, 0x2000
	s_add_u32 s34, s34, 0x164000
	v_lshl_add_u64 v[238:239], s[54:55], 0, v[0:1]
	s_addc_u32 s35, s35, 0
	s_add_i32 s52, s53, s19
	global_load_lds_dwordx4 v[238:239], off
	v_lshl_add_u64 v[238:239], s[34:35], 0, v[134:135]
	s_mov_b32 m0, s52
	v_lshl_add_u64 v[154:155], v[154:155], 0, s[14:15]
	global_load_lds_dwordx4 v[238:239], off
	v_lshl_add_u64 v[238:239], s[34:35], 0, v[0:1]
	s_add_i32 m0, s52, 0x2000
	s_nop 0
	global_load_lds_dwordx4 v[238:239], off
	s_mov_b32 m0, s61
	s_nop 0
	global_load_lds_dwordx4 v[154:155], off
	v_lshl_add_u64 v[154:155], v[236:237], 0, s[14:15]
	s_mov_b32 m0, s62
	s_nop 0
	global_load_lds_dwordx4 v[154:155], off
	s_waitcnt vmcnt(8)
	s_waitcnt lgkmcnt(0)
	s_barrier
	s_setprio 1
	v_mfma_f32_16x16x32_bf16 v[64:67], v[146:149], v[196:199], v[64:67]
	v_mfma_f32_16x16x32_bf16 v[60:63], v[172:175], v[196:199], v[60:63]
	v_mfma_f32_16x16x32_bf16 v[44:47], v[172:175], v[204:207], v[44:47]
	v_mfma_f32_16x16x32_bf16 v[48:51], v[146:149], v[204:207], v[48:51]
	v_mfma_f32_16x16x32_bf16 v[32:35], v[146:149], v[212:215], v[32:35]
	v_mfma_f32_16x16x32_bf16 v[28:31], v[172:175], v[212:215], v[28:31]
	v_mfma_f32_16x16x32_bf16 v[12:15], v[172:175], v[228:231], v[12:15]
	v_mfma_f32_16x16x32_bf16 v[16:19], v[146:149], v[228:231], v[16:19]
	v_mfma_f32_16x16x32_bf16 v[64:67], v[150:153], v[200:203], v[64:67]
	v_mfma_f32_16x16x32_bf16 v[60:63], v[176:179], v[200:203], v[60:63]
	v_mfma_f32_16x16x32_bf16 v[44:47], v[176:179], v[208:211], v[44:47]
	v_mfma_f32_16x16x32_bf16 v[48:51], v[150:153], v[208:211], v[48:51]
	v_mfma_f32_16x16x32_bf16 v[32:35], v[150:153], v[216:219], v[32:35]
	v_mfma_f32_16x16x32_bf16 v[28:31], v[176:179], v[216:219], v[28:31]
	v_mfma_f32_16x16x32_bf16 v[12:15], v[176:179], v[232:235], v[12:15]
	v_mfma_f32_16x16x32_bf16 v[16:19], v[150:153], v[232:235], v[16:19]
	v_mfma_f32_16x16x32_bf16 v[56:59], v[180:183], v[196:199], v[56:59]
	v_mfma_f32_16x16x32_bf16 v[52:55], v[188:191], v[196:199], v[52:55]
	v_mfma_f32_16x16x32_bf16 v[36:39], v[188:191], v[204:207], v[36:39]
	v_mfma_f32_16x16x32_bf16 v[40:43], v[180:183], v[204:207], v[40:43]
	v_mfma_f32_16x16x32_bf16 v[24:27], v[180:183], v[212:215], v[24:27]
	v_mfma_f32_16x16x32_bf16 v[20:23], v[188:191], v[212:215], v[20:23]
	v_mfma_f32_16x16x32_bf16 v[4:7], v[188:191], v[228:231], v[4:7]
	v_mfma_f32_16x16x32_bf16 v[8:11], v[180:183], v[228:231], v[8:11]
	v_mfma_f32_16x16x32_bf16 v[56:59], v[184:187], v[200:203], v[56:59]
	v_mfma_f32_16x16x32_bf16 v[52:55], v[192:195], v[200:203], v[52:55]
	v_mfma_f32_16x16x32_bf16 v[36:39], v[192:195], v[208:211], v[36:39]
	v_mfma_f32_16x16x32_bf16 v[40:43], v[184:187], v[208:211], v[40:43]
	v_mfma_f32_16x16x32_bf16 v[24:27], v[184:187], v[216:219], v[24:27]
	v_mfma_f32_16x16x32_bf16 v[20:23], v[192:195], v[216:219], v[20:23]
	v_mfma_f32_16x16x32_bf16 v[4:7], v[192:195], v[232:235], v[4:7]
	v_mfma_f32_16x16x32_bf16 v[8:11], v[184:187], v[232:235], v[8:11]
	s_setprio 0
	s_barrier
	s_add_i32 s77, s77, 2
	s_add_u32 s71, s71, 0x2c0000
	s_addc_u32 s76, s76, 0
	s_add_u32 s50, s50, 0x100
	s_addc_u32 s51, s51, 0
	s_cmp_gt_u32 s77, 29
	s_cbranch_scc0 .LBB0_169
	s_and_b64 vcc, exec, s[28:29]
	s_cbranch_vccz .LBB0_172
	s_barrier

.LBB0_243:
	s_add_u32 s34, s44, 0xfff80080
	s_addc_u32 s35, s45, -1
	s_add_i32 s52, 0, 0x10000
	s_cmp_eq_u32 vcc_hi, 28
	s_cselect_b32 s47, s36, s35
	s_cselect_b32 s46, s37, s34
	s_cselect_b32 s35, s55, vcc_lo
	s_cselect_b32 s34, s57, s63
	s_add_i32 s68, 0, 0x14000
	v_add_u32_e32 v144, s52, v155
	v_add_u32_e32 v180, s68, v155
	ds_read_b128 v[132:135], v144
	ds_read_b128 v[136:139], v144 offset:1024
	ds_read_b128 v[140:143], v144 offset:2048
	ds_read_b128 v[144:147], v144 offset:3072
	ds_read_b128 v[176:179], v180
	ds_read_b128 v[182:185], v180 offset:1024
	ds_read_b128 v[186:189], v180 offset:2048
	ds_read_b128 v[190:193], v180 offset:3072
	v_lshl_add_u64 v[218:219], s[44:45], 0, v[172:173]
	s_add_i32 m0, s69, 0xc000
	ds_read_b128 v[194:197], v181
	ds_read_b128 v[198:201], v181 offset:1024
	ds_read_b128 v[202:205], v181 offset:2048
	ds_read_b128 v[206:209], v181 offset:3072
	ds_read_b128 v[210:213], v181 offset:4096
	ds_read_b128 v[214:217], v181 offset:5120
	ds_read_b128 v[228:231], v181 offset:6144
	ds_read_b128 v[232:235], v181 offset:7168
	global_load_lds_dwordx4 v[218:219], off
	v_lshl_add_u64 v[218:219], s[44:45], 0, v[174:175]
	s_add_i32 m0, s69, 0xe000
	s_nop 0
	global_load_lds_dwordx4 v[218:219], off
	s_waitcnt vmcnt(8)
	s_waitcnt lgkmcnt(0)
	s_barrier
	s_setprio 1
	v_mfma_f32_16x16x32_bf16 v[128:131], v[132:135], v[194:197], v[128:131]
	v_mfma_f32_16x16x32_bf16 v[124:127], v[140:143], v[194:197], v[124:127]
	v_mfma_f32_16x16x32_bf16 v[108:111], v[140:143], v[202:205], v[108:111]
	v_mfma_f32_16x16x32_bf16 v[112:115], v[132:135], v[202:205], v[112:115]
	v_mfma_f32_16x16x32_bf16 v[96:99], v[132:135], v[210:213], v[96:99]
	v_mfma_f32_16x16x32_bf16 v[92:95], v[140:143], v[210:213], v[92:95]
	v_mfma_f32_16x16x32_bf16 v[76:79], v[140:143], v[228:231], v[76:79]
	v_mfma_f32_16x16x32_bf16 v[80:83], v[132:135], v[228:231], v[80:83]
	v_mfma_f32_16x16x32_bf16 v[128:131], v[136:139], v[198:201], v[128:131]
	v_mfma_f32_16x16x32_bf16 v[124:127], v[144:147], v[198:201], v[124:127]
	v_mfma_f32_16x16x32_bf16 v[108:111], v[144:147], v[206:209], v[108:111]
	v_mfma_f32_16x16x32_bf16 v[112:115], v[136:139], v[206:209], v[112:115]
	v_mfma_f32_16x16x32_bf16 v[96:99], v[136:139], v[214:217], v[96:99]
	v_mfma_f32_16x16x32_bf16 v[92:95], v[144:147], v[214:217], v[92:95]
	v_mfma_f32_16x16x32_bf16 v[76:79], v[144:147], v[232:235], v[76:79]
	v_mfma_f32_16x16x32_bf16 v[80:83], v[136:139], v[232:235], v[80:83]
	v_mfma_f32_16x16x32_bf16 v[120:123], v[176:179], v[194:197], v[120:123]
	v_mfma_f32_16x16x32_bf16 v[116:119], v[186:189], v[194:197], v[116:119]
	v_mfma_f32_16x16x32_bf16 v[100:103], v[186:189], v[202:205], v[100:103]
	v_mfma_f32_16x16x32_bf16 v[104:107], v[176:179], v[202:205], v[104:107]
	v_mfma_f32_16x16x32_bf16 v[88:91], v[176:179], v[210:213], v[88:91]
	v_mfma_f32_16x16x32_bf16 v[84:87], v[186:189], v[210:213], v[84:87]
	v_mfma_f32_16x16x32_bf16 v[68:71], v[186:189], v[228:231], v[68:71]
	v_mfma_f32_16x16x32_bf16 v[72:75], v[176:179], v[228:231], v[72:75]
	v_mfma_f32_16x16x32_bf16 v[120:123], v[182:185], v[198:201], v[120:123]
	v_mfma_f32_16x16x32_bf16 v[116:119], v[190:193], v[198:201], v[116:119]
	v_mfma_f32_16x16x32_bf16 v[100:103], v[190:193], v[206:209], v[100:103]
	v_mfma_f32_16x16x32_bf16 v[104:107], v[182:185], v[206:209], v[104:107]
	v_mfma_f32_16x16x32_bf16 v[88:91], v[182:185], v[214:217], v[88:91]
	v_mfma_f32_16x16x32_bf16 v[84:87], v[190:193], v[214:217], v[84:87]
	v_mfma_f32_16x16x32_bf16 v[68:71], v[190:193], v[232:235], v[68:71]
	v_mfma_f32_16x16x32_bf16 v[72:75], v[182:185], v[232:235], v[72:75]
	s_setprio 0
	s_barrier
	s_add_i32 s52, s52, s2
	v_lshl_add_u64 v[218:219], s[34:35], 0, v[150:151]
	s_mov_b32 m0, s52
	ds_read_b128 v[194:197], v181 offset:16384
	ds_read_b128 v[198:201], v181 offset:17408
	ds_read_b128 v[202:205], v181 offset:18432
	ds_read_b128 v[206:209], v181 offset:19456
	ds_read_b128 v[210:213], v181 offset:20480
	ds_read_b128 v[214:217], v181 offset:21504
	ds_read_b128 v[228:231], v181 offset:22528
	ds_read_b128 v[232:235], v181 offset:23552
	global_load_lds_dwordx4 v[218:219], off
	s_add_i32 m0, s52, 0x2000
	s_add_u32 s52, s34, 0x4000
	v_lshl_add_u64 v[218:219], s[34:35], 0, v[0:1]
	s_addc_u32 s53, s35, 0
	s_add_i32 s68, s68, s2
	global_load_lds_dwordx4 v[218:219], off
	v_lshl_add_u64 v[218:219], s[52:53], 0, v[150:151]
	s_mov_b32 m0, s68
	v_lshl_add_u64 v[236:237], s[46:47], 0, v[148:149]
	global_load_lds_dwordx4 v[218:219], off
	v_lshl_add_u64 v[218:219], s[52:53], 0, v[0:1]
	s_add_i32 m0, s68, 0x2000
	s_nop 0
	global_load_lds_dwordx4 v[218:219], off
	v_lshl_add_u64 v[218:219], s[46:47], 0, v[152:153]
	s_mov_b32 m0, s69
	s_nop 0
	global_load_lds_dwordx4 v[218:219], off
	s_mov_b32 m0, s71
	s_nop 0
	global_load_lds_dwordx4 v[236:237], off
	s_waitcnt vmcnt(8)
	s_waitcnt lgkmcnt(0)
	s_barrier
	s_setprio 1
	v_mfma_f32_16x16x32_bf16 v[64:67], v[132:135], v[194:197], v[64:67]
	v_mfma_f32_16x16x32_bf16 v[60:63], v[140:143], v[194:197], v[60:63]
	v_mfma_f32_16x16x32_bf16 v[44:47], v[140:143], v[202:205], v[44:47]
	v_mfma_f32_16x16x32_bf16 v[48:51], v[132:135], v[202:205], v[48:51]
	v_mfma_f32_16x16x32_bf16 v[32:35], v[132:135], v[210:213], v[32:35]
	v_mfma_f32_16x16x32_bf16 v[28:31], v[140:143], v[210:213], v[28:31]
	v_mfma_f32_16x16x32_bf16 v[12:15], v[140:143], v[228:231], v[12:15]
	v_mfma_f32_16x16x32_bf16 v[16:19], v[132:135], v[228:231], v[16:19]
	v_mfma_f32_16x16x32_bf16 v[64:67], v[136:139], v[198:201], v[64:67]
	v_mfma_f32_16x16x32_bf16 v[60:63], v[144:147], v[198:201], v[60:63]
	v_mfma_f32_16x16x32_bf16 v[44:47], v[144:147], v[206:209], v[44:47]
	v_mfma_f32_16x16x32_bf16 v[48:51], v[136:139], v[206:209], v[48:51]
	v_mfma_f32_16x16x32_bf16 v[32:35], v[136:139], v[214:217], v[32:35]
	v_mfma_f32_16x16x32_bf16 v[28:31], v[144:147], v[214:217], v[28:31]
	v_mfma_f32_16x16x32_bf16 v[12:15], v[144:147], v[232:235], v[12:15]
	v_mfma_f32_16x16x32_bf16 v[16:19], v[136:139], v[232:235], v[16:19]
	v_mfma_f32_16x16x32_bf16 v[56:59], v[176:179], v[194:197], v[56:59]
	v_mfma_f32_16x16x32_bf16 v[52:55], v[186:189], v[194:197], v[52:55]
	v_mfma_f32_16x16x32_bf16 v[36:39], v[186:189], v[202:205], v[36:39]
	v_mfma_f32_16x16x32_bf16 v[40:43], v[176:179], v[202:205], v[40:43]
	v_mfma_f32_16x16x32_bf16 v[24:27], v[176:179], v[210:213], v[24:27]
	v_mfma_f32_16x16x32_bf16 v[20:23], v[186:189], v[210:213], v[20:23]
	v_mfma_f32_16x16x32_bf16 v[4:7], v[186:189], v[228:231], v[4:7]
	v_mfma_f32_16x16x32_bf16 v[8:11], v[176:179], v[228:231], v[8:11]
	v_mfma_f32_16x16x32_bf16 v[56:59], v[182:185], v[198:201], v[56:59]
	v_mfma_f32_16x16x32_bf16 v[52:55], v[190:193], v[198:201], v[52:55]
	v_mfma_f32_16x16x32_bf16 v[36:39], v[190:193], v[206:209], v[36:39]
	v_mfma_f32_16x16x32_bf16 v[40:43], v[182:185], v[206:209], v[40:43]
	v_mfma_f32_16x16x32_bf16 v[24:27], v[182:185], v[214:217], v[24:27]
	v_mfma_f32_16x16x32_bf16 v[20:23], v[190:193], v[214:217], v[20:23]
	v_mfma_f32_16x16x32_bf16 v[4:7], v[190:193], v[232:235], v[4:7]
	v_mfma_f32_16x16x32_bf16 v[8:11], v[182:185], v[232:235], v[8:11]
	s_setprio 0
	s_barrier
	s_add_i32 s52, 0, 0x18000
	s_add_i32 s53, 0, 0x1c000
	v_add_u32_e32 v144, s52, v155
	v_add_u32_e32 v180, s53, v155
	ds_read_b128 v[132:135], v144
	ds_read_b128 v[136:139], v144 offset:1024
	ds_read_b128 v[140:143], v144 offset:2048
	ds_read_b128 v[144:147], v144 offset:3072
	ds_read_b128 v[176:179], v180
	ds_read_b128 v[182:185], v180 offset:1024
	ds_read_b128 v[186:189], v180 offset:2048
	ds_read_b128 v[190:193], v180 offset:3072
	s_add_u32 s46, s46, 0x80000
	s_addc_u32 s47, s47, 0
	s_mov_b32 m0, s88
	v_lshl_add_u64 v[238:239], s[46:47], 0, v[152:153]
	ds_read_b128 v[194:197], v181 offset:32768
	ds_read_b128 v[198:201], v181 offset:33792
	ds_read_b128 v[202:205], v181 offset:34816
	ds_read_b128 v[206:209], v181 offset:35840
	ds_read_b128 v[210:213], v181 offset:36864
	ds_read_b128 v[214:217], v181 offset:37888
	ds_read_b128 v[228:231], v181 offset:38912
	ds_read_b128 v[232:235], v181 offset:39936
	global_load_lds_dwordx4 v[238:239], off
	v_lshl_add_u64 v[238:239], s[46:47], 0, v[148:149]
	s_mov_b32 m0, s96
	s_nop 0
	global_load_lds_dwordx4 v[238:239], off
	s_waitcnt vmcnt(8)
	s_waitcnt lgkmcnt(0)
	s_barrier
	s_setprio 1
	v_mfma_f32_16x16x32_bf16 v[128:131], v[132:135], v[194:197], v[128:131]
	v_mfma_f32_16x16x32_bf16 v[124:127], v[140:143], v[194:197], v[124:127]
	v_mfma_f32_16x16x32_bf16 v[108:111], v[140:143], v[202:205], v[108:111]
	v_mfma_f32_16x16x32_bf16 v[112:115], v[132:135], v[202:205], v[112:115]
	v_mfma_f32_16x16x32_bf16 v[96:99], v[132:135], v[210:213], v[96:99]
	v_mfma_f32_16x16x32_bf16 v[92:95], v[140:143], v[210:213], v[92:95]
	v_mfma_f32_16x16x32_bf16 v[76:79], v[140:143], v[228:231], v[76:79]
	v_mfma_f32_16x16x32_bf16 v[80:83], v[132:135], v[228:231], v[80:83]
	v_mfma_f32_16x16x32_bf16 v[128:131], v[136:139], v[198:201], v[128:131]
	v_mfma_f32_16x16x32_bf16 v[124:127], v[144:147], v[198:201], v[124:127]
	v_mfma_f32_16x16x32_bf16 v[108:111], v[144:147], v[206:209], v[108:111]
	v_mfma_f32_16x16x32_bf16 v[112:115], v[136:139], v[206:209], v[112:115]
	v_mfma_f32_16x16x32_bf16 v[96:99], v[136:139], v[214:217], v[96:99]
	v_mfma_f32_16x16x32_bf16 v[92:95], v[144:147], v[214:217], v[92:95]
	v_mfma_f32_16x16x32_bf16 v[76:79], v[144:147], v[232:235], v[76:79]
	v_mfma_f32_16x16x32_bf16 v[80:83], v[136:139], v[232:235], v[80:83]
	v_mfma_f32_16x16x32_bf16 v[120:123], v[176:179], v[194:197], v[120:123]
	v_mfma_f32_16x16x32_bf16 v[116:119], v[186:189], v[194:197], v[116:119]
	v_mfma_f32_16x16x32_bf16 v[100:103], v[186:189], v[202:205], v[100:103]
	v_mfma_f32_16x16x32_bf16 v[104:107], v[176:179], v[202:205], v[104:107]
	v_mfma_f32_16x16x32_bf16 v[88:91], v[176:179], v[210:213], v[88:91]
	v_mfma_f32_16x16x32_bf16 v[84:87], v[186:189], v[210:213], v[84:87]
	v_mfma_f32_16x16x32_bf16 v[68:71], v[186:189], v[228:231], v[68:71]
	v_mfma_f32_16x16x32_bf16 v[72:75], v[176:179], v[228:231], v[72:75]
	v_mfma_f32_16x16x32_bf16 v[120:123], v[182:185], v[198:201], v[120:123]
	v_mfma_f32_16x16x32_bf16 v[116:119], v[190:193], v[198:201], v[116:119]
	v_mfma_f32_16x16x32_bf16 v[100:103], v[190:193], v[206:209], v[100:103]
	v_mfma_f32_16x16x32_bf16 v[104:107], v[182:185], v[206:209], v[104:107]
	v_mfma_f32_16x16x32_bf16 v[88:91], v[182:185], v[214:217], v[88:91]
	v_mfma_f32_16x16x32_bf16 v[84:87], v[190:193], v[214:217], v[84:87]
	v_mfma_f32_16x16x32_bf16 v[68:71], v[190:193], v[232:235], v[68:71]
	v_mfma_f32_16x16x32_bf16 v[72:75], v[182:185], v[232:235], v[72:75]
	s_setprio 0
	s_barrier
	s_add_u32 s46, s34, 0x70000
	s_addc_u32 s47, s35, 0
	s_add_i32 s52, s52, s2
	v_lshl_add_u64 v[238:239], s[46:47], 0, v[150:151]
	s_mov_b32 m0, s52
	ds_read_b128 v[194:197], v181 offset:49152
	ds_read_b128 v[198:201], v181 offset:50176
	ds_read_b128 v[202:205], v181 offset:51200
	ds_read_b128 v[206:209], v181 offset:52224
	ds_read_b128 v[210:213], v181 offset:53248
	ds_read_b128 v[214:217], v181 offset:54272
	ds_read_b128 v[228:231], v181 offset:55296
	ds_read_b128 v[232:235], v181 offset:56320
	global_load_lds_dwordx4 v[238:239], off
	s_add_i32 m0, s52, 0x2000
	s_add_u32 s34, s34, 0x74000
	v_lshl_add_u64 v[238:239], s[46:47], 0, v[0:1]
	s_addc_u32 s35, s35, 0
	s_add_i32 s46, s53, s2
	global_load_lds_dwordx4 v[238:239], off
	v_lshl_add_u64 v[238:239], s[34:35], 0, v[150:151]
	s_mov_b32 m0, s46
	v_lshl_add_u64 v[218:219], v[218:219], 0, s[14:15]
	global_load_lds_dwordx4 v[238:239], off
	v_lshl_add_u64 v[238:239], s[34:35], 0, v[0:1]
	s_add_i32 m0, s46, 0x2000
	s_nop 0
	global_load_lds_dwordx4 v[238:239], off
	s_mov_b32 m0, s97
	s_nop 0
	global_load_lds_dwordx4 v[218:219], off
	v_lshl_add_u64 v[218:219], v[236:237], 0, s[14:15]
	s_mov_b32 m0, s76
	s_nop 0
	global_load_lds_dwordx4 v[218:219], off
	s_waitcnt vmcnt(8)
	s_waitcnt lgkmcnt(0)
	s_barrier
	s_setprio 1
	v_mfma_f32_16x16x32_bf16 v[64:67], v[132:135], v[194:197], v[64:67]
	v_mfma_f32_16x16x32_bf16 v[60:63], v[140:143], v[194:197], v[60:63]
	v_mfma_f32_16x16x32_bf16 v[44:47], v[140:143], v[202:205], v[44:47]
	v_mfma_f32_16x16x32_bf16 v[48:51], v[132:135], v[202:205], v[48:51]
	v_mfma_f32_16x16x32_bf16 v[32:35], v[132:135], v[210:213], v[32:35]
	v_mfma_f32_16x16x32_bf16 v[28:31], v[140:143], v[210:213], v[28:31]
	v_mfma_f32_16x16x32_bf16 v[12:15], v[140:143], v[228:231], v[12:15]
	v_mfma_f32_16x16x32_bf16 v[16:19], v[132:135], v[228:231], v[16:19]
	v_mfma_f32_16x16x32_bf16 v[64:67], v[136:139], v[198:201], v[64:67]
	v_mfma_f32_16x16x32_bf16 v[60:63], v[144:147], v[198:201], v[60:63]
	v_mfma_f32_16x16x32_bf16 v[44:47], v[144:147], v[206:209], v[44:47]
	v_mfma_f32_16x16x32_bf16 v[48:51], v[136:139], v[206:209], v[48:51]
	v_mfma_f32_16x16x32_bf16 v[32:35], v[136:139], v[214:217], v[32:35]
	v_mfma_f32_16x16x32_bf16 v[28:31], v[144:147], v[214:217], v[28:31]
	v_mfma_f32_16x16x32_bf16 v[12:15], v[144:147], v[232:235], v[12:15]
	v_mfma_f32_16x16x32_bf16 v[16:19], v[136:139], v[232:235], v[16:19]
	v_mfma_f32_16x16x32_bf16 v[56:59], v[176:179], v[194:197], v[56:59]
	v_mfma_f32_16x16x32_bf16 v[52:55], v[186:189], v[194:197], v[52:55]
	v_mfma_f32_16x16x32_bf16 v[36:39], v[186:189], v[202:205], v[36:39]
	v_mfma_f32_16x16x32_bf16 v[40:43], v[176:179], v[202:205], v[40:43]
	v_mfma_f32_16x16x32_bf16 v[24:27], v[176:179], v[210:213], v[24:27]
	v_mfma_f32_16x16x32_bf16 v[20:23], v[186:189], v[210:213], v[20:23]
	v_mfma_f32_16x16x32_bf16 v[4:7], v[186:189], v[228:231], v[4:7]
	v_mfma_f32_16x16x32_bf16 v[8:11], v[176:179], v[228:231], v[8:11]
	v_mfma_f32_16x16x32_bf16 v[56:59], v[182:185], v[198:201], v[56:59]
	v_mfma_f32_16x16x32_bf16 v[52:55], v[190:193], v[198:201], v[52:55]
	v_mfma_f32_16x16x32_bf16 v[36:39], v[190:193], v[206:209], v[36:39]
	v_mfma_f32_16x16x32_bf16 v[40:43], v[182:185], v[206:209], v[40:43]
	v_mfma_f32_16x16x32_bf16 v[24:27], v[182:185], v[214:217], v[24:27]
	v_mfma_f32_16x16x32_bf16 v[20:23], v[190:193], v[214:217], v[20:23]
	v_mfma_f32_16x16x32_bf16 v[4:7], v[190:193], v[232:235], v[4:7]
	v_mfma_f32_16x16x32_bf16 v[8:11], v[182:185], v[232:235], v[8:11]
	s_setprio 0
	s_barrier
	s_add_i32 vcc_hi, vcc_hi, 2
	s_add_u32 s63, s63, 0xe0000
	s_addc_u32 vcc_lo, vcc_lo, 0
	s_add_u32 s44, s44, 0x100
	s_addc_u32 s45, s45, 0
	s_cmp_gt_u32 vcc_hi, 29
	s_cbranch_scc0 .LBB0_243
	s_and_b64 vcc, exec, s[28:29]
	s_cbranch_vccz .LBB0_246
	s_barrier

.LBB0_559:
	s_add_i32 vcc_lo, s34, 2
	s_add_u32 s35, s42, 0x80
	s_addc_u32 s52, s43, 0
	s_add_i32 s53, 0, 0x10000
	s_cmp_eq_u32 s77, s34
	s_cselect_b32 s57, s51, s52
	s_cselect_b32 s56, s50, s35
	s_cselect_b32 s35, s36, s97
	s_cselect_b32 s34, s37, s49
	s_add_i32 s68, 0, 0x14000
	v_add_u32_e32 v136, s53, v200
	v_add_u32_e32 v186, s68, v200
	ds_read_b128 v[116:119], v136
	ds_read_b128 v[120:123], v136 offset:1024
	ds_read_b128 v[124:127], v136 offset:2048
	ds_read_b128 v[136:139], v136 offset:3072
	ds_read_b128 v[148:151], v186
	ds_read_b128 v[152:155], v186 offset:1024
	ds_read_b128 v[182:185], v186 offset:2048
	ds_read_b128 v[186:189], v186 offset:3072
	v_lshl_add_u64 v[198:199], s[42:43], 0, v[178:179]
	s_add_i32 m0, s59, 0xc000
	ds_read_b128 v[190:193], v202
	ds_read_b128 v[194:197], v202 offset:1024
	ds_read_b128 v[204:207], v202 offset:2048
	ds_read_b128 v[208:211], v202 offset:3072
	ds_read_b128 v[212:215], v202 offset:4096
	ds_read_b128 v[216:219], v202 offset:5120
	ds_read_b128 v[228:231], v202 offset:6144
	ds_read_b128 v[232:235], v202 offset:7168
	global_load_lds_dwordx4 v[198:199], off
	v_lshl_add_u64 v[198:199], s[42:43], 0, v[180:181]
	s_add_i32 m0, s59, 0xe000
	s_nop 0
	global_load_lds_dwordx4 v[198:199], off
	s_waitcnt vmcnt(8)
	s_waitcnt lgkmcnt(0)
	s_barrier
	s_setprio 1
	v_mfma_f32_16x16x32_bf16 v[144:147], v[116:119], v[190:193], v[144:147]
	v_mfma_f32_16x16x32_bf16 v[140:143], v[124:127], v[190:193], v[140:143]
	v_mfma_f32_16x16x32_bf16 v[108:111], v[124:127], v[204:207], v[108:111]
	v_mfma_f32_16x16x32_bf16 v[112:115], v[116:119], v[204:207], v[112:115]
	v_mfma_f32_16x16x32_bf16 v[96:99], v[116:119], v[212:215], v[96:99]
	v_mfma_f32_16x16x32_bf16 v[92:95], v[124:127], v[212:215], v[92:95]
	v_mfma_f32_16x16x32_bf16 v[76:79], v[124:127], v[228:231], v[76:79]
	v_mfma_f32_16x16x32_bf16 v[80:83], v[116:119], v[228:231], v[80:83]
	v_mfma_f32_16x16x32_bf16 v[144:147], v[120:123], v[194:197], v[144:147]
	v_mfma_f32_16x16x32_bf16 v[140:143], v[136:139], v[194:197], v[140:143]
	v_mfma_f32_16x16x32_bf16 v[108:111], v[136:139], v[208:211], v[108:111]
	v_mfma_f32_16x16x32_bf16 v[112:115], v[120:123], v[208:211], v[112:115]
	v_mfma_f32_16x16x32_bf16 v[96:99], v[120:123], v[216:219], v[96:99]
	v_mfma_f32_16x16x32_bf16 v[92:95], v[136:139], v[216:219], v[92:95]
	v_mfma_f32_16x16x32_bf16 v[76:79], v[136:139], v[232:235], v[76:79]
	v_mfma_f32_16x16x32_bf16 v[80:83], v[120:123], v[232:235], v[80:83]
	v_mfma_f32_16x16x32_bf16 v[132:135], v[148:151], v[190:193], v[132:135]
	v_mfma_f32_16x16x32_bf16 v[128:131], v[182:185], v[190:193], v[128:131]
	v_mfma_f32_16x16x32_bf16 v[100:103], v[182:185], v[204:207], v[100:103]
	v_mfma_f32_16x16x32_bf16 v[104:107], v[148:151], v[204:207], v[104:107]
	v_mfma_f32_16x16x32_bf16 v[88:91], v[148:151], v[212:215], v[88:91]
	v_mfma_f32_16x16x32_bf16 v[84:87], v[182:185], v[212:215], v[84:87]
	v_mfma_f32_16x16x32_bf16 v[68:71], v[182:185], v[228:231], v[68:71]
	v_mfma_f32_16x16x32_bf16 v[72:75], v[148:151], v[228:231], v[72:75]
	v_mfma_f32_16x16x32_bf16 v[132:135], v[152:155], v[194:197], v[132:135]
	v_mfma_f32_16x16x32_bf16 v[128:131], v[186:189], v[194:197], v[128:131]
	v_mfma_f32_16x16x32_bf16 v[100:103], v[186:189], v[208:211], v[100:103]
	v_mfma_f32_16x16x32_bf16 v[104:107], v[152:155], v[208:211], v[104:107]
	v_mfma_f32_16x16x32_bf16 v[88:91], v[152:155], v[216:219], v[88:91]
	v_mfma_f32_16x16x32_bf16 v[84:87], v[186:189], v[216:219], v[84:87]
	v_mfma_f32_16x16x32_bf16 v[68:71], v[186:189], v[232:235], v[68:71]
	v_mfma_f32_16x16x32_bf16 v[72:75], v[152:155], v[232:235], v[72:75]
	s_setprio 0
	s_barrier
	s_add_i32 s52, s53, s58
	v_lshl_add_u64 v[198:199], s[34:35], 0, v[174:175]
	s_mov_b32 m0, s52
	ds_read_b128 v[190:193], v202 offset:16384
	ds_read_b128 v[194:197], v202 offset:17408
	ds_read_b128 v[204:207], v202 offset:18432
	ds_read_b128 v[208:211], v202 offset:19456
	ds_read_b128 v[212:215], v202 offset:20480
	ds_read_b128 v[216:219], v202 offset:21504
	ds_read_b128 v[228:231], v202 offset:22528
	ds_read_b128 v[232:235], v202 offset:23552
	global_load_lds_dwordx4 v[198:199], off
	s_add_i32 m0, s52, 0x2000
	s_add_u32 s52, s34, 0x4000
	v_lshl_add_u64 v[198:199], s[34:35], 0, v[0:1]
	s_addc_u32 s53, s35, 0
	s_add_i32 s68, s68, s58
	global_load_lds_dwordx4 v[198:199], off
	v_lshl_add_u64 v[198:199], s[52:53], 0, v[174:175]
	s_mov_b32 m0, s68
	v_lshl_add_u64 v[236:237], s[56:57], 0, v[172:173]
	global_load_lds_dwordx4 v[198:199], off
	v_lshl_add_u64 v[198:199], s[52:53], 0, v[0:1]
	s_add_i32 m0, s68, 0x2000
	s_nop 0
	global_load_lds_dwordx4 v[198:199], off
	v_lshl_add_u64 v[198:199], s[56:57], 0, v[176:177]
	s_mov_b32 m0, s59
	s_nop 0
	global_load_lds_dwordx4 v[198:199], off
	s_mov_b32 m0, s60
	s_nop 0
	global_load_lds_dwordx4 v[236:237], off
	s_waitcnt vmcnt(8)
	s_waitcnt lgkmcnt(0)
	s_barrier
	s_setprio 1
	v_mfma_f32_16x16x32_bf16 v[64:67], v[116:119], v[190:193], v[64:67]
	v_mfma_f32_16x16x32_bf16 v[60:63], v[124:127], v[190:193], v[60:63]
	v_mfma_f32_16x16x32_bf16 v[44:47], v[124:127], v[204:207], v[44:47]
	v_mfma_f32_16x16x32_bf16 v[48:51], v[116:119], v[204:207], v[48:51]
	v_mfma_f32_16x16x32_bf16 v[32:35], v[116:119], v[212:215], v[32:35]
	v_mfma_f32_16x16x32_bf16 v[28:31], v[124:127], v[212:215], v[28:31]
	v_mfma_f32_16x16x32_bf16 v[12:15], v[124:127], v[228:231], v[12:15]
	v_mfma_f32_16x16x32_bf16 v[16:19], v[116:119], v[228:231], v[16:19]
	v_mfma_f32_16x16x32_bf16 v[64:67], v[120:123], v[194:197], v[64:67]
	v_mfma_f32_16x16x32_bf16 v[60:63], v[136:139], v[194:197], v[60:63]
	v_mfma_f32_16x16x32_bf16 v[44:47], v[136:139], v[208:211], v[44:47]
	v_mfma_f32_16x16x32_bf16 v[48:51], v[120:123], v[208:211], v[48:51]
	v_mfma_f32_16x16x32_bf16 v[32:35], v[120:123], v[216:219], v[32:35]
	v_mfma_f32_16x16x32_bf16 v[28:31], v[136:139], v[216:219], v[28:31]
	v_mfma_f32_16x16x32_bf16 v[12:15], v[136:139], v[232:235], v[12:15]
	v_mfma_f32_16x16x32_bf16 v[16:19], v[120:123], v[232:235], v[16:19]
	v_mfma_f32_16x16x32_bf16 v[56:59], v[148:151], v[190:193], v[56:59]
	v_mfma_f32_16x16x32_bf16 v[52:55], v[182:185], v[190:193], v[52:55]
	v_mfma_f32_16x16x32_bf16 v[36:39], v[182:185], v[204:207], v[36:39]
	v_mfma_f32_16x16x32_bf16 v[40:43], v[148:151], v[204:207], v[40:43]
	v_mfma_f32_16x16x32_bf16 v[24:27], v[148:151], v[212:215], v[24:27]
	v_mfma_f32_16x16x32_bf16 v[20:23], v[182:185], v[212:215], v[20:23]
	v_mfma_f32_16x16x32_bf16 v[4:7], v[182:185], v[228:231], v[4:7]
	v_mfma_f32_16x16x32_bf16 v[8:11], v[148:151], v[228:231], v[8:11]
	v_mfma_f32_16x16x32_bf16 v[56:59], v[152:155], v[194:197], v[56:59]
	v_mfma_f32_16x16x32_bf16 v[52:55], v[186:189], v[194:197], v[52:55]
	v_mfma_f32_16x16x32_bf16 v[36:39], v[186:189], v[208:211], v[36:39]
	v_mfma_f32_16x16x32_bf16 v[40:43], v[152:155], v[208:211], v[40:43]
	v_mfma_f32_16x16x32_bf16 v[24:27], v[152:155], v[216:219], v[24:27]
	v_mfma_f32_16x16x32_bf16 v[20:23], v[186:189], v[216:219], v[20:23]
	v_mfma_f32_16x16x32_bf16 v[4:7], v[186:189], v[232:235], v[4:7]
	v_mfma_f32_16x16x32_bf16 v[8:11], v[152:155], v[232:235], v[8:11]
	s_setprio 0
	s_barrier
	s_add_i32 s68, 0, 0x18000
	s_add_i32 vcc_hi, 0, 0x1c000
	v_add_u32_e32 v136, s68, v200
	v_add_u32_e32 v186, vcc_hi, v200
	ds_read_b128 v[116:119], v136
	ds_read_b128 v[120:123], v136 offset:1024
	ds_read_b128 v[124:127], v136 offset:2048
	ds_read_b128 v[136:139], v136 offset:3072
	ds_read_b128 v[148:151], v186
	ds_read_b128 v[152:155], v186 offset:1024
	ds_read_b128 v[182:185], v186 offset:2048
	ds_read_b128 v[186:189], v186 offset:3072
	s_add_u32 s52, s56, s26
	s_addc_u32 s53, s57, 0
	s_mov_b32 m0, s61
	v_lshl_add_u64 v[238:239], s[52:53], 0, v[176:177]
	ds_read_b128 v[190:193], v202 offset:32768
	ds_read_b128 v[194:197], v202 offset:33792
	ds_read_b128 v[204:207], v202 offset:34816
	ds_read_b128 v[208:211], v202 offset:35840
	ds_read_b128 v[212:215], v202 offset:36864
	ds_read_b128 v[216:219], v202 offset:37888
	ds_read_b128 v[228:231], v202 offset:38912
	ds_read_b128 v[232:235], v202 offset:39936
	global_load_lds_dwordx4 v[238:239], off
	v_lshl_add_u64 v[238:239], s[52:53], 0, v[172:173]
	s_mov_b32 m0, s62
	s_nop 0
	global_load_lds_dwordx4 v[238:239], off
	s_waitcnt vmcnt(8)
	s_waitcnt lgkmcnt(0)
	s_barrier
	s_setprio 1
	v_mfma_f32_16x16x32_bf16 v[144:147], v[116:119], v[190:193], v[144:147]
	v_mfma_f32_16x16x32_bf16 v[140:143], v[124:127], v[190:193], v[140:143]
	v_mfma_f32_16x16x32_bf16 v[108:111], v[124:127], v[204:207], v[108:111]
	v_mfma_f32_16x16x32_bf16 v[112:115], v[116:119], v[204:207], v[112:115]
	v_mfma_f32_16x16x32_bf16 v[96:99], v[116:119], v[212:215], v[96:99]
	v_mfma_f32_16x16x32_bf16 v[92:95], v[124:127], v[212:215], v[92:95]
	v_mfma_f32_16x16x32_bf16 v[76:79], v[124:127], v[228:231], v[76:79]
	v_mfma_f32_16x16x32_bf16 v[80:83], v[116:119], v[228:231], v[80:83]
	v_mfma_f32_16x16x32_bf16 v[144:147], v[120:123], v[194:197], v[144:147]
	v_mfma_f32_16x16x32_bf16 v[140:143], v[136:139], v[194:197], v[140:143]
	v_mfma_f32_16x16x32_bf16 v[108:111], v[136:139], v[208:211], v[108:111]
	v_mfma_f32_16x16x32_bf16 v[112:115], v[120:123], v[208:211], v[112:115]
	v_mfma_f32_16x16x32_bf16 v[96:99], v[120:123], v[216:219], v[96:99]
	v_mfma_f32_16x16x32_bf16 v[92:95], v[136:139], v[216:219], v[92:95]
	v_mfma_f32_16x16x32_bf16 v[76:79], v[136:139], v[232:235], v[76:79]
	v_mfma_f32_16x16x32_bf16 v[80:83], v[120:123], v[232:235], v[80:83]
	v_mfma_f32_16x16x32_bf16 v[132:135], v[148:151], v[190:193], v[132:135]
	v_mfma_f32_16x16x32_bf16 v[128:131], v[182:185], v[190:193], v[128:131]
	v_mfma_f32_16x16x32_bf16 v[100:103], v[182:185], v[204:207], v[100:103]
	v_mfma_f32_16x16x32_bf16 v[104:107], v[148:151], v[204:207], v[104:107]
	v_mfma_f32_16x16x32_bf16 v[88:91], v[148:151], v[212:215], v[88:91]
	v_mfma_f32_16x16x32_bf16 v[84:87], v[182:185], v[212:215], v[84:87]
	v_mfma_f32_16x16x32_bf16 v[68:71], v[182:185], v[228:231], v[68:71]
	v_mfma_f32_16x16x32_bf16 v[72:75], v[148:151], v[228:231], v[72:75]
	v_mfma_f32_16x16x32_bf16 v[132:135], v[152:155], v[194:197], v[132:135]
	v_mfma_f32_16x16x32_bf16 v[128:131], v[186:189], v[194:197], v[128:131]
	v_mfma_f32_16x16x32_bf16 v[100:103], v[186:189], v[208:211], v[100:103]
	v_mfma_f32_16x16x32_bf16 v[104:107], v[152:155], v[208:211], v[104:107]
	v_mfma_f32_16x16x32_bf16 v[88:91], v[152:155], v[216:219], v[88:91]
	v_mfma_f32_16x16x32_bf16 v[84:87], v[186:189], v[216:219], v[84:87]
	v_mfma_f32_16x16x32_bf16 v[68:71], v[186:189], v[232:235], v[68:71]
	v_mfma_f32_16x16x32_bf16 v[72:75], v[152:155], v[232:235], v[72:75]
	s_setprio 0
	s_barrier
	s_add_u32 s52, s34, 0x40000
	s_addc_u32 s53, s35, 0
	s_add_i32 s56, s68, s58
	v_lshl_add_u64 v[238:239], s[52:53], 0, v[174:175]
	s_mov_b32 m0, s56
	ds_read_b128 v[190:193], v202 offset:49152
	ds_read_b128 v[194:197], v202 offset:50176
	ds_read_b128 v[204:207], v202 offset:51200
	ds_read_b128 v[208:211], v202 offset:52224
	ds_read_b128 v[212:215], v202 offset:53248
	ds_read_b128 v[216:219], v202 offset:54272
	ds_read_b128 v[228:231], v202 offset:55296
	ds_read_b128 v[232:235], v202 offset:56320
	global_load_lds_dwordx4 v[238:239], off
	s_add_i32 m0, s56, 0x2000
	s_add_u32 s34, s34, 0x44000
	v_lshl_add_u64 v[238:239], s[52:53], 0, v[0:1]
	s_addc_u32 s35, s35, 0
	s_add_i32 s52, vcc_hi, s58
	global_load_lds_dwordx4 v[238:239], off
	v_lshl_add_u64 v[238:239], s[34:35], 0, v[174:175]
	s_mov_b32 m0, s52
	v_lshl_add_u64 v[198:199], v[198:199], 0, s[14:15]
	global_load_lds_dwordx4 v[238:239], off
	v_lshl_add_u64 v[238:239], s[34:35], 0, v[0:1]
	s_add_i32 m0, s52, 0x2000
	s_nop 0
	global_load_lds_dwordx4 v[238:239], off
	s_mov_b32 m0, s71
	s_nop 0
	global_load_lds_dwordx4 v[198:199], off
	v_lshl_add_u64 v[198:199], v[236:237], 0, s[14:15]
	s_mov_b32 m0, s76
	s_nop 0
	global_load_lds_dwordx4 v[198:199], off
	s_waitcnt vmcnt(8)
	s_waitcnt lgkmcnt(0)
	s_barrier
	s_setprio 1
	v_mfma_f32_16x16x32_bf16 v[64:67], v[116:119], v[190:193], v[64:67]
	v_mfma_f32_16x16x32_bf16 v[60:63], v[124:127], v[190:193], v[60:63]
	v_mfma_f32_16x16x32_bf16 v[44:47], v[124:127], v[204:207], v[44:47]
	v_mfma_f32_16x16x32_bf16 v[48:51], v[116:119], v[204:207], v[48:51]
	v_mfma_f32_16x16x32_bf16 v[32:35], v[116:119], v[212:215], v[32:35]
	v_mfma_f32_16x16x32_bf16 v[28:31], v[124:127], v[212:215], v[28:31]
	v_mfma_f32_16x16x32_bf16 v[12:15], v[124:127], v[228:231], v[12:15]
	v_mfma_f32_16x16x32_bf16 v[16:19], v[116:119], v[228:231], v[16:19]
	v_mfma_f32_16x16x32_bf16 v[64:67], v[120:123], v[194:197], v[64:67]
	v_mfma_f32_16x16x32_bf16 v[60:63], v[136:139], v[194:197], v[60:63]
	v_mfma_f32_16x16x32_bf16 v[44:47], v[136:139], v[208:211], v[44:47]
	v_mfma_f32_16x16x32_bf16 v[48:51], v[120:123], v[208:211], v[48:51]
	v_mfma_f32_16x16x32_bf16 v[32:35], v[120:123], v[216:219], v[32:35]
	v_mfma_f32_16x16x32_bf16 v[28:31], v[136:139], v[216:219], v[28:31]
	v_mfma_f32_16x16x32_bf16 v[12:15], v[136:139], v[232:235], v[12:15]
	v_mfma_f32_16x16x32_bf16 v[16:19], v[120:123], v[232:235], v[16:19]
	v_mfma_f32_16x16x32_bf16 v[56:59], v[148:151], v[190:193], v[56:59]
	v_mfma_f32_16x16x32_bf16 v[52:55], v[182:185], v[190:193], v[52:55]
	v_mfma_f32_16x16x32_bf16 v[36:39], v[182:185], v[204:207], v[36:39]
	v_mfma_f32_16x16x32_bf16 v[40:43], v[148:151], v[204:207], v[40:43]
	v_mfma_f32_16x16x32_bf16 v[24:27], v[148:151], v[212:215], v[24:27]
	v_mfma_f32_16x16x32_bf16 v[20:23], v[182:185], v[212:215], v[20:23]
	v_mfma_f32_16x16x32_bf16 v[4:7], v[182:185], v[228:231], v[4:7]
	v_mfma_f32_16x16x32_bf16 v[8:11], v[148:151], v[228:231], v[8:11]
	v_mfma_f32_16x16x32_bf16 v[56:59], v[152:155], v[194:197], v[56:59]
	v_mfma_f32_16x16x32_bf16 v[52:55], v[186:189], v[194:197], v[52:55]
	v_mfma_f32_16x16x32_bf16 v[36:39], v[186:189], v[208:211], v[36:39]
	v_mfma_f32_16x16x32_bf16 v[40:43], v[152:155], v[208:211], v[40:43]
	v_mfma_f32_16x16x32_bf16 v[24:27], v[152:155], v[216:219], v[24:27]
	v_mfma_f32_16x16x32_bf16 v[20:23], v[186:189], v[216:219], v[20:23]
	v_mfma_f32_16x16x32_bf16 v[4:7], v[186:189], v[232:235], v[4:7]
	v_mfma_f32_16x16x32_bf16 v[8:11], v[152:155], v[232:235], v[8:11]
	s_setprio 0
	s_barrier
	s_add_u32 s49, s49, 0x80000
	s_addc_u32 s97, s97, 0
	s_add_u32 s42, s42, 0x100
	s_addc_u32 s43, s43, 0
	s_cmp_ge_u32 vcc_lo, s69
	s_mov_b32 s34, vcc_lo
	s_cbranch_scc0 .LBB0_559
	s_and_b64 vcc, exec, s[46:47]
	s_cbranch_vccz .LBB0_562
	s_barrier
